# Up epilogue rstd table now filled by the leading wave half (one lane per row) before the barrier it already waits at; no extra barrier in the epilogue
# speedup vs baseline: 1.0144x; 1.0030x over previous
; __device__ __forceinline__ int lane_id_v() { int l; asm volatile("v_mbcnt_lo_u32_b32 %0, -1, 0\n\tv_mbcnt_hi_u32_b32 %0, -1, %0" : "=v"(l)); return l; }
; #define PG8_BAR __builtin_amdgcn_s_barrier()
; #define LAS __attribute__((address_space(3)))
; template <class Epi, class Sched, bool ALIGN_EPI, bool SP2>
; __device__ __forceinline__ void gemm_phase(PG8_LAS unsigned char* lds, const Gemm g, const Sched& S, const Epi& E, int wid) {
;     ...
;         if constexpr (ALIGN_EPI) { if (wr == 0) PG8_BAR; }
;     __device__ __forceinline__ void operator()(const f32x4 (&acc)[2][2][4][2], const pg8::Unit& u, int wr, int wc, int fr_, int fq_) const {
;         const int lane_ = pg8::lane_id_v(); const int fr = lane_ & 15, fq = lane_ >> 4;
;         const int lrow0 = u.pm * 256 + wr * 64 + fr;
;         const int b = batch_of(rowbase + u.pm * 256);
;         f32x4 sv[2][2];
; #pragma unroll
;         for (int bj = 0; bj < 2; ++bj)
; #pragma unroll
;             for (int n = 0; n < 2; ++n) sv[bj][n] = *(const LAS f32x4*)(xl + 16384 + (bj * 128 + wc * 32 + 8 * fq + 4 * n) * 4);
;         float rs8[8]; rows_rstd8_lds(xl, wr * 64 + fr, fq, rs8);
;         const int hcol = u.pn * 128 + wc * 32 + 8 * fq;
; #pragma unroll
;         for (int ai = 0; ai < 2; ++ai)
; #pragma unroll
;             for (int m = 0; m < 4; ++m) {
;                 const int lr = lrow0 + ai * 128 + m * 16;
;                 const float rs = rs8[ai * 4 + m];
;                 const f32x4 g0 = acc[ai][0][m][0] * rs + sv[0][0], g1 = acc[ai][0][m][1] * rs + sv[0][1];
;                 const f32x4 u0 = acc[ai][1][m][0] * rs + sv[1][0], u1 = acc[ai][1][m][1] * rs + sv[1][1];
.LBB0_377:
	s_and_b64 vcc, exec, s[20:21]
	s_cbranch_vccz .LBB0_379
	v_mbcnt_lo_u32_b32 v228, -1, 0
	v_mbcnt_hi_u32_b32 v228, -1, v228
	s_lshl_b32 s26, s15, 1
	v_add_u32_e32 v224, s26, v228
	v_lshlrev_b32_e32 v227, 2, v224
	v_lshlrev_b32_e32 v224, 6, v224
	v_add_u32_e32 v224, 0x22400, v224
	v_add_u32_e32 v227, 0x26800, v227
	ds_read_b128 v[216:219], v224
	ds_read_b128 v[220:223], v224 offset:16
	ds_read_b128 v[230:233], v224 offset:32
	ds_read_b128 v[242:245], v224 offset:48
	v_mov_b32_e32 v226, 0x358637bd
	s_waitcnt lgkmcnt(0)
	v_add_f32_e32 v216, v216, v217
	v_add_f32_e32 v218, v218, v219
	v_add_f32_e32 v220, v220, v221
	v_add_f32_e32 v222, v222, v223
	v_add_f32_e32 v230, v230, v231
	v_add_f32_e32 v232, v232, v233
	v_add_f32_e32 v242, v242, v243
	v_add_f32_e32 v244, v244, v245
	v_add_f32_e32 v216, v216, v218
	v_add_f32_e32 v220, v220, v222
	v_add_f32_e32 v230, v230, v232
	v_add_f32_e32 v242, v242, v244
	v_add_f32_e32 v216, v216, v220
	v_add_f32_e32 v230, v230, v242
	v_add_f32_e32 v225, v230, v216
	v_fma_f32 v225, v225, s16, v226
	v_rsq_f32_e32 v225, v225
	s_nop 0
	ds_write_b32 v227, v225
	s_waitcnt lgkmcnt(0)
	s_barrier
.LBB0_379:
	v_mbcnt_lo_u32_b32 v228, -1, 0
	v_mbcnt_hi_u32_b32 v228, -1, v228
	v_and_b32_e32 v224, 15, v228
	v_add_u32_e32 v224, s91, v224
	v_lshlrev_b32_e32 v224, 2, v224
	v_add_u32_e32 v224, 0x26800, v224
	ds_read_b32 v208, v224
	ds_read_b32 v209, v224 offset:64
	ds_read_b32 v210, v224 offset:128
	ds_read_b32 v211, v224 offset:192
	ds_read_b32 v212, v224 offset:512
	ds_read_b32 v213, v224 offset:576
	ds_read_b32 v214, v224 offset:640
	ds_read_b32 v215, v224 offset:704
	s_waitcnt lgkmcnt(0)
	v_mbcnt_lo_u32_b32 v158, -1, 0
	v_mbcnt_hi_u32_b32 v158, -1, v158
	s_add_i32 s23, s23, s91
	v_and_b32_e32 v159, 15, v158
	v_or_b32_e32 v165, s23, v159
	v_ashrrev_i32_e32 v167, 4, v158
	v_readlane_b32 s26, v252, 22
	s_add_i32 s23, 0, 0x22400
	v_lshl_add_u32 v80, v167, 5, s26
	ds_read_b128 v[92:95], v80
	ds_read_b128 v[88:91], v80 offset:16
	ds_read_b128 v[84:87], v80 offset:512
	ds_read_b128 v[80:83], v80 offset:528
	s_mov_b32 s26, 0x358637bd
	s_lshl_b32 s2, s2, 7
	s_waitcnt lgkmcnt(0)
	s_waitcnt lgkmcnt(0)
	s_or_b32 s2, s2, s15
	s_mov_b64 s[76:77], s[62:63]
	s_waitcnt lgkmcnt(0)
	s_waitcnt lgkmcnt(0)
	s_nop 0
	s_nop 0
	s_nop 0
	v_mov_b32_e32 v172, v208
	s_waitcnt lgkmcnt(0)
	v_mov_b32_e32 v170, v209
	v_pk_fma_f32 v[126:127], v[126:127], v[170:171], v[94:95] op_sel_hi:[1,0,1]
	v_pk_fma_f32 v[124:125], v[124:125], v[170:171], v[92:93] op_sel_hi:[1,0,1]
	s_waitcnt lgkmcnt(0)
	v_pk_fma_f32 v[116:117], v[116:117], v[170:171], v[84:85] op_sel_hi:[1,0,1]
	v_pk_fma_f32 v[118:119], v[118:119], v[170:171], v[86:87] op_sel_hi:[1,0,1]
	v_pk_mul_f32 v[116:117], v[124:125], v[116:117]
	v_pk_fma_f32 v[120:121], v[120:121], v[170:171], v[88:89] op_sel_hi:[1,0,1]
	s_waitcnt lgkmcnt(0)
	v_pk_mul_f32 v[118:119], v[126:127], v[118:119]
	v_pk_fma_f32 v[112:113], v[112:113], v[170:171], v[80:81] op_sel_hi:[1,0,1]
	v_pk_fma_f32 v[122:123], v[122:123], v[170:171], v[90:91] op_sel_hi:[1,0,1]
	v_pk_mul_f32 v[112:113], v[120:121], v[112:113]
	s_waitcnt lgkmcnt(0)
	v_pk_fma_f32 v[114:115], v[114:115], v[170:171], v[82:83] op_sel_hi:[1,0,1]
	v_pk_mul_f32 v[114:115], v[122:123], v[114:115]
	s_nop 0
	s_nop 0
	v_mov_b32_e32 v168, v210
	v_pk_fma_f32 v[110:111], v[110:111], v[168:169], v[94:95] op_sel_hi:[1,0,1]
	v_pk_fma_f32 v[108:109], v[108:109], v[168:169], v[92:93] op_sel_hi:[1,0,1]
	v_pk_fma_f32 v[100:101], v[100:101], v[168:169], v[84:85] op_sel_hi:[1,0,1]
	s_waitcnt lgkmcnt(0)
	v_mov_b32_e32 v166, v211
	v_pk_mul_f32 v[100:101], v[108:109], v[100:101]
	v_pk_fma_f32 v[102:103], v[102:103], v[168:169], v[86:87] op_sel_hi:[1,0,1]
	s_waitcnt lgkmcnt(0)
	v_pk_fma_f32 v[104:105], v[104:105], v[168:169], v[88:89] op_sel_hi:[1,0,1]
	v_pk_mul_f32 v[102:103], v[110:111], v[102:103]
	v_pk_fma_f32 v[96:97], v[96:97], v[168:169], v[80:81] op_sel_hi:[1,0,1]
	v_pk_fma_f32 v[106:107], v[106:107], v[168:169], v[90:91] op_sel_hi:[1,0,1]
	s_waitcnt lgkmcnt(0)
	v_pk_mul_f32 v[96:97], v[104:105], v[96:97]
	v_pk_fma_f32 v[98:99], v[98:99], v[168:169], v[82:83] op_sel_hi:[1,0,1]
	v_pk_fma_f32 v[78:79], v[78:79], v[166:167], v[94:95] op_sel_hi:[1,0,1]
	v_pk_mul_f32 v[98:99], v[106:107], v[98:99]
	s_waitcnt lgkmcnt(0)
	v_pk_fma_f32 v[76:77], v[76:77], v[166:167], v[92:93] op_sel_hi:[1,0,1]
	v_pk_fma_f32 v[68:69], v[68:69], v[166:167], v[84:85] op_sel_hi:[1,0,1]
	v_pk_mul_f32 v[68:69], v[76:77], v[68:69]
	v_pk_fma_f32 v[70:71], v[70:71], v[166:167], v[86:87] op_sel_hi:[1,0,1]
	v_pk_fma_f32 v[72:73], v[72:73], v[166:167], v[88:89] op_sel_hi:[1,0,1]
	v_pk_mul_f32 v[70:71], v[78:79], v[70:71]
	v_mov_b32_e32 v164, v212
	v_pk_fma_f32 v[64:65], v[64:65], v[166:167], v[80:81] op_sel_hi:[1,0,1]
	v_pk_fma_f32 v[74:75], v[74:75], v[166:167], v[90:91] op_sel_hi:[1,0,1]
	v_pk_mul_f32 v[64:65], v[72:73], v[64:65]
	s_waitcnt lgkmcnt(0)
	v_pk_fma_f32 v[142:143], v[142:143], v[172:173], v[94:95] op_sel_hi:[1,0,1]
	v_pk_fma_f32 v[140:141], v[140:141], v[172:173], v[92:93] op_sel_hi:[1,0,1]
	v_pk_fma_f32 v[132:133], v[132:133], v[172:173], v[84:85] op_sel_hi:[1,0,1]
	v_mov_b32_e32 v162, v213
	v_pk_fma_f32 v[138:139], v[138:139], v[172:173], v[90:91] op_sel_hi:[1,0,1]
	v_pk_fma_f32 v[136:137], v[136:137], v[172:173], v[88:89] op_sel_hi:[1,0,1]
	v_pk_fma_f32 v[134:135], v[134:135], v[172:173], v[86:87] op_sel_hi:[1,0,1]
	v_pk_fma_f32 v[128:129], v[128:129], v[172:173], v[80:81] op_sel_hi:[1,0,1]
	v_pk_fma_f32 v[130:131], v[130:131], v[172:173], v[82:83] op_sel_hi:[1,0,1]
	v_pk_mul_f32 v[172:173], v[140:141], s[88:89] op_sel_hi:[1,0]
	v_pk_mul_f32 v[132:133], v[140:141], v[132:133]
	v_pk_mul_f32 v[140:141], v[142:143], s[88:89] op_sel_hi:[1,0]
	s_waitcnt lgkmcnt(0)
; __device__ __forceinline__ unsigned cvt_pk_bf16(float lo, float hi) { unsigned r; asm volatile("v_cvt_pk_bf16_f32 %0, %1, %2" : "=v"(r) : "v"(lo), "v"(hi)); return r; }
; __device__ __forceinline__ f32x2 silu_mul_pk(f32x2 g, f32x2 u) {
;     const f32x2 t = g * (-1.4426950409f);
;     f32x2 e; e.x = __builtin_amdgcn_exp2f(t.x); e.y = __builtin_amdgcn_exp2f(t.y);
;     const f32x2 d = e + 1.0f;
;     f32x2 r; r.x = __builtin_amdgcn_rcpf(d.x); r.y = __builtin_amdgcn_rcpf(d.y);
;     return (g * u) * r;
; }
;     __device__ __forceinline__ void operator()(const f32x4 (&acc)[2][2][4][2], const pg8::Unit& u, int wr, int wc, int fr_, int fq_) const {
;     ...
;             for (int m = 0; m < 4; ++m) {
;                 const int lr = lrow0 + ai * 128 + m * 16;
;                 const float rs = rs8[ai * 4 + m];
;                 const f32x4 g0 = acc[ai][0][m][0] * rs + sv[0][0], g1 = acc[ai][0][m][1] * rs + sv[0][1];
;                 const f32x4 u0 = acc[ai][1][m][0] * rs + sv[1][0], u1 = acc[ai][1][m][1] * rs + sv[1][1];
;                 const f32x2 ha = pg8::silu_mul_pk((f32x2){g0[0], g0[1]}, (f32x2){u0[0], u0[1]}), hb = pg8::silu_mul_pk((f32x2){g0[2], g0[3]}, (f32x2){u0[2], u0[3]});
;                 const f32x2 hc = pg8::silu_mul_pk((f32x2){g1[0], g1[1]}, (f32x2){u1[0], u1[1]}), hd = pg8::silu_mul_pk((f32x2){g1[2], g1[3]}, (f32x2){u1[2], u1[3]});
;                 u32x4 w; w.x = cvt_pk_bf16(ha.x, ha.y); w.y = cvt_pk_bf16(hb.x, hb.y); w.z = cvt_pk_bf16(hc.x, hc.y); w.w = cvt_pk_bf16(hd.x, hd.y);
;                 *(u32x4*)(H + (size_t)lr * FF + hcol) = w;
;             }
	v_exp_f32_e32 v140, v140
	v_exp_f32_e32 v141, v141
	s_nop 0
	v_pk_add_f32 v[140:141], v[140:141], 1.0 op_sel_hi:[1,0]
	v_rcp_f32_e32 v140, v140
	v_rcp_f32_e32 v141, v141
	v_pk_mul_f32 v[134:135], v[142:143], v[134:135]
	v_exp_f32_e32 v172, v172
	v_pk_mul_f32 v[134:135], v[134:135], v[140:141]
	v_pk_mul_f32 v[140:141], v[136:137], s[88:89] op_sel_hi:[1,0]
	v_exp_f32_e32 v173, v173
	v_exp_f32_e32 v140, v140
	v_exp_f32_e32 v141, v141
	v_pk_mul_f32 v[128:129], v[136:137], v[128:129]
	v_pk_mul_f32 v[136:137], v[138:139], s[88:89] op_sel_hi:[1,0]
	s_waitcnt lgkmcnt(0)
	v_exp_f32_e32 v136, v136
	v_exp_f32_e32 v137, v137
	v_pk_add_f32 v[172:173], v[172:173], 1.0 op_sel_hi:[1,0]
	v_pk_add_f32 v[140:141], v[140:141], 1.0 op_sel_hi:[1,0]
	v_rcp_f32_e32 v172, v172
	v_rcp_f32_e32 v173, v173
	v_rcp_f32_e32 v140, v140
	v_rcp_f32_e32 v141, v141
	v_pk_add_f32 v[136:137], v[136:137], 1.0 op_sel_hi:[1,0]
	s_waitcnt lgkmcnt(0)
	v_rcp_f32_e32 v136, v136
	v_rcp_f32_e32 v137, v137
	v_lshl_add_u32 v174, v167, 3, s2
	v_pk_mul_f32 v[132:133], v[132:133], v[172:173]
	v_pk_mul_f32 v[130:131], v[138:139], v[130:131]
	v_pk_mul_f32 v[128:129], v[128:129], v[140:141]
	v_ashrrev_i32_e32 v175, 31, v174
	v_pk_mul_f32 v[130:131], v[130:131], v[136:137]
	v_cvt_pk_bf16_f32 v132, v132, v133
	v_cvt_pk_bf16_f32 v133, v134, v135
	v_cvt_pk_bf16_f32 v134, v128, v129
	v_mov_b64_e32 v[128:129], s[30:31]
	s_movk_i32 s2, 0x1600
	v_cvt_pk_bf16_f32 v135, v130, v131
	v_mad_i64_i32 v[136:137], s[26:27], v165, s2, v[128:129]
	v_lshlrev_b64 v[130:131], 1, v[174:175]
	v_lshl_add_u64 v[136:137], v[136:137], 0, v[130:131]
	global_store_dwordx4 v[136:137], v[132:135], off
	v_pk_fma_f32 v[66:67], v[66:67], v[166:167], v[82:83] op_sel_hi:[1,0,1]
	v_pk_fma_f32 v[62:63], v[62:63], v[164:165], v[94:95] op_sel_hi:[1,0,1]
	v_pk_mul_f32 v[132:133], v[124:125], s[88:89] op_sel_hi:[1,0]
	v_pk_mul_f32 v[124:125], v[126:127], s[88:89] op_sel_hi:[1,0]
	v_exp_f32_e32 v132, v132
	v_exp_f32_e32 v124, v124
	v_exp_f32_e32 v125, v125
	v_exp_f32_e32 v133, v133
	v_or_b32_e32 v134, 16, v165
	v_pk_mul_f32 v[66:67], v[74:75], v[66:67]
	v_pk_add_f32 v[124:125], v[124:125], 1.0 op_sel_hi:[1,0]
	v_pk_add_f32 v[132:133], v[132:133], 1.0 op_sel_hi:[1,0]
	v_rcp_f32_e32 v124, v124
	v_rcp_f32_e32 v125, v125
	v_rcp_f32_e32 v132, v132
	v_rcp_f32_e32 v133, v133
	v_pk_fma_f32 v[60:61], v[60:61], v[164:165], v[92:93] op_sel_hi:[1,0,1]
	v_pk_mul_f32 v[118:119], v[118:119], v[124:125]
	v_pk_mul_f32 v[124:125], v[120:121], s[88:89] op_sel_hi:[1,0]
	v_pk_mul_f32 v[116:117], v[116:117], v[132:133]
	v_exp_f32_e32 v124, v124
	v_exp_f32_e32 v125, v125
	v_pk_fma_f32 v[52:53], v[52:53], v[164:165], v[84:85] op_sel_hi:[1,0,1]
	v_pk_fma_f32 v[54:55], v[54:55], v[164:165], v[86:87] op_sel_hi:[1,0,1]
	v_pk_mul_f32 v[52:53], v[60:61], v[52:53]
	v_pk_add_f32 v[124:125], v[124:125], 1.0 op_sel_hi:[1,0]
	v_pk_fma_f32 v[56:57], v[56:57], v[164:165], v[88:89] op_sel_hi:[1,0,1]
	v_rcp_f32_e32 v124, v124
	v_rcp_f32_e32 v125, v125
	v_pk_mul_f32 v[54:55], v[62:63], v[54:55]
	v_pk_fma_f32 v[48:49], v[48:49], v[164:165], v[80:81] op_sel_hi:[1,0,1]
	v_pk_fma_f32 v[58:59], v[58:59], v[164:165], v[90:91] op_sel_hi:[1,0,1]
	v_pk_mul_f32 v[120:121], v[112:113], v[124:125]
	v_pk_mul_f32 v[112:113], v[122:123], s[88:89] op_sel_hi:[1,0]
	v_pk_mul_f32 v[48:49], v[56:57], v[48:49]
	v_exp_f32_e32 v112, v112
	v_exp_f32_e32 v113, v113
	v_pk_fma_f32 v[50:51], v[50:51], v[164:165], v[82:83] op_sel_hi:[1,0,1]
	v_pk_fma_f32 v[46:47], v[46:47], v[162:163], v[94:95] op_sel_hi:[1,0,1]
	v_pk_mul_f32 v[50:51], v[58:59], v[50:51]
	v_pk_add_f32 v[112:113], v[112:113], 1.0 op_sel_hi:[1,0]
	v_pk_fma_f32 v[44:45], v[44:45], v[162:163], v[92:93] op_sel_hi:[1,0,1]
	v_rcp_f32_e32 v112, v112
	v_rcp_f32_e32 v113, v113
	v_pk_fma_f32 v[36:37], v[36:37], v[162:163], v[84:85] op_sel_hi:[1,0,1]
	v_pk_fma_f32 v[38:39], v[38:39], v[162:163], v[86:87] op_sel_hi:[1,0,1]
	v_pk_mul_f32 v[36:37], v[44:45], v[36:37]
	v_pk_mul_f32 v[122:123], v[114:115], v[112:113]
	v_cvt_pk_bf16_f32 v112, v116, v117
	v_mad_i64_i32 v[116:117], s[26:27], v134, s2, v[128:129]
	v_cvt_pk_bf16_f32 v113, v118, v119
	v_lshl_add_u64 v[116:117], v[116:117], 0, v[130:131]
	v_cvt_pk_bf16_f32 v114, v120, v121
	v_cvt_pk_bf16_f32 v115, v122, v123
	global_store_dwordx4 v[116:117], v[112:115], off
	v_pk_fma_f32 v[40:41], v[40:41], v[162:163], v[88:89] op_sel_hi:[1,0,1]
	v_pk_mul_f32 v[38:39], v[46:47], v[38:39]
	v_pk_mul_f32 v[112:113], v[108:109], s[88:89] op_sel_hi:[1,0]
	v_pk_mul_f32 v[108:109], v[110:111], s[88:89] op_sel_hi:[1,0]
	v_exp_f32_e32 v112, v112
	v_exp_f32_e32 v108, v108
	v_exp_f32_e32 v109, v109
	v_exp_f32_e32 v113, v113
	v_or_b32_e32 v114, 32, v165
	v_pk_fma_f32 v[32:33], v[32:33], v[162:163], v[80:81] op_sel_hi:[1,0,1]
	v_pk_add_f32 v[108:109], v[108:109], 1.0 op_sel_hi:[1,0]
	v_pk_add_f32 v[112:113], v[112:113], 1.0 op_sel_hi:[1,0]
	v_rcp_f32_e32 v108, v108
	v_rcp_f32_e32 v109, v109
	v_rcp_f32_e32 v112, v112
	v_rcp_f32_e32 v113, v113
	v_pk_fma_f32 v[42:43], v[42:43], v[162:163], v[90:91] op_sel_hi:[1,0,1]
	v_pk_mul_f32 v[102:103], v[102:103], v[108:109]
	v_pk_mul_f32 v[108:109], v[104:105], s[88:89] op_sel_hi:[1,0]
	v_pk_mul_f32 v[100:101], v[100:101], v[112:113]
	v_exp_f32_e32 v108, v108
	v_exp_f32_e32 v109, v109
	v_pk_mul_f32 v[32:33], v[40:41], v[32:33]
	v_pk_add_f32 v[108:109], v[108:109], 1.0 op_sel_hi:[1,0]
	v_pk_fma_f32 v[34:35], v[34:35], v[162:163], v[82:83] op_sel_hi:[1,0,1]
	v_rcp_f32_e32 v108, v108
	v_rcp_f32_e32 v109, v109
	v_pk_mul_f32 v[34:35], v[42:43], v[34:35]
	v_pk_mul_f32 v[104:105], v[96:97], v[108:109]
	v_pk_mul_f32 v[96:97], v[106:107], s[88:89] op_sel_hi:[1,0]
	v_exp_f32_e32 v96, v96
; __device__ __forceinline__ unsigned cvt_pk_bf16(float lo, float hi) { unsigned r; asm volatile("v_cvt_pk_bf16_f32 %0, %1, %2" : "=v"(r) : "v"(lo), "v"(hi)); return r; }
; __device__ __forceinline__ f32x2 silu_mul_pk(f32x2 g, f32x2 u) {
;     const f32x2 t = g * (-1.4426950409f);
;     f32x2 e; e.x = __builtin_amdgcn_exp2f(t.x); e.y = __builtin_amdgcn_exp2f(t.y);
;     const f32x2 d = e + 1.0f;
;     f32x2 r; r.x = __builtin_amdgcn_rcpf(d.x); r.y = __builtin_amdgcn_rcpf(d.y);
;     return (g * u) * r;
; }
;     __device__ __forceinline__ void operator()(const f32x4 (&acc)[2][2][4][2], const pg8::Unit& u, int wr, int wc, int fr_, int fq_) const {
;     ...
;             for (int m = 0; m < 4; ++m) {
;                 const int lr = lrow0 + ai * 128 + m * 16;
;                 const float rs = rs8[ai * 4 + m];
;                 const f32x4 g0 = acc[ai][0][m][0] * rs + sv[0][0], g1 = acc[ai][0][m][1] * rs + sv[0][1];
;                 const f32x4 u0 = acc[ai][1][m][0] * rs + sv[1][0], u1 = acc[ai][1][m][1] * rs + sv[1][1];
;                 const f32x2 ha = pg8::silu_mul_pk((f32x2){g0[0], g0[1]}, (f32x2){u0[0], u0[1]}), hb = pg8::silu_mul_pk((f32x2){g0[2], g0[3]}, (f32x2){u0[2], u0[3]});
;                 const f32x2 hc = pg8::silu_mul_pk((f32x2){g1[0], g1[1]}, (f32x2){u1[0], u1[1]}), hd = pg8::silu_mul_pk((f32x2){g1[2], g1[3]}, (f32x2){u1[2], u1[3]});
;                 u32x4 w; w.x = cvt_pk_bf16(ha.x, ha.y); w.y = cvt_pk_bf16(hb.x, hb.y); w.z = cvt_pk_bf16(hc.x, hc.y); w.w = cvt_pk_bf16(hd.x, hd.y);
;                 *(u32x4*)(H + (size_t)lr * FF + hcol) = w;
;             }
	v_exp_f32_e32 v97, v97
	v_mov_b32_e32 v160, v214
	v_pk_fma_f32 v[30:31], v[30:31], v[160:161], v[94:95] op_sel_hi:[1,0,1]
	v_pk_fma_f32 v[28:29], v[28:29], v[160:161], v[92:93] op_sel_hi:[1,0,1]
	v_pk_add_f32 v[96:97], v[96:97], 1.0 op_sel_hi:[1,0]
	v_pk_fma_f32 v[20:21], v[20:21], v[160:161], v[84:85] op_sel_hi:[1,0,1]
	v_rcp_f32_e32 v96, v96
	v_rcp_f32_e32 v97, v97
	v_pk_mul_f32 v[20:21], v[28:29], v[20:21]
	v_pk_fma_f32 v[22:23], v[22:23], v[160:161], v[86:87] op_sel_hi:[1,0,1]
	v_pk_fma_f32 v[24:25], v[24:25], v[160:161], v[88:89] op_sel_hi:[1,0,1]
	v_pk_mul_f32 v[106:107], v[98:99], v[96:97]
	v_cvt_pk_bf16_f32 v96, v100, v101
	v_mad_i64_i32 v[100:101], s[26:27], v114, s2, v[128:129]
	v_cvt_pk_bf16_f32 v97, v102, v103
	v_lshl_add_u64 v[100:101], v[100:101], 0, v[130:131]
	v_cvt_pk_bf16_f32 v98, v104, v105
	v_cvt_pk_bf16_f32 v99, v106, v107
	global_store_dwordx4 v[100:101], v[96:99], off
	v_pk_mul_f32 v[22:23], v[30:31], v[22:23]
	v_pk_fma_f32 v[16:17], v[16:17], v[160:161], v[80:81] op_sel_hi:[1,0,1]
	v_pk_mul_f32 v[96:97], v[76:77], s[88:89] op_sel_hi:[1,0]
	v_pk_mul_f32 v[76:77], v[78:79], s[88:89] op_sel_hi:[1,0]
	v_exp_f32_e32 v96, v96
	v_exp_f32_e32 v76, v76
	v_exp_f32_e32 v77, v77
	v_exp_f32_e32 v97, v97
	v_or_b32_e32 v98, 48, v165
	v_pk_fma_f32 v[26:27], v[26:27], v[160:161], v[90:91] op_sel_hi:[1,0,1]
	v_pk_add_f32 v[76:77], v[76:77], 1.0 op_sel_hi:[1,0]
	v_pk_add_f32 v[96:97], v[96:97], 1.0 op_sel_hi:[1,0]
	v_rcp_f32_e32 v76, v76
	v_rcp_f32_e32 v77, v77
	v_rcp_f32_e32 v96, v96
	v_rcp_f32_e32 v97, v97
	v_pk_mul_f32 v[16:17], v[24:25], v[16:17]
	v_pk_mul_f32 v[70:71], v[70:71], v[76:77]
	v_pk_mul_f32 v[76:77], v[72:73], s[88:89] op_sel_hi:[1,0]
	v_pk_mul_f32 v[68:69], v[68:69], v[96:97]
	v_exp_f32_e32 v76, v76
	v_exp_f32_e32 v77, v77
	v_pk_fma_f32 v[18:19], v[18:19], v[160:161], v[82:83] op_sel_hi:[1,0,1]
	v_pk_add_f32 v[76:77], v[76:77], 1.0 op_sel_hi:[1,0]
	v_rcp_f32_e32 v76, v76
	v_rcp_f32_e32 v77, v77
	v_pk_mul_f32 v[18:19], v[26:27], v[18:19]
	v_pk_mul_f32 v[72:73], v[64:65], v[76:77]
	v_pk_mul_f32 v[64:65], v[74:75], s[88:89] op_sel_hi:[1,0]
	v_exp_f32_e32 v64, v64
	v_exp_f32_e32 v65, v65
	v_mov_b32_e32 v158, v215
	v_pk_fma_f32 v[14:15], v[14:15], v[158:159], v[94:95] op_sel_hi:[1,0,1]
	v_pk_fma_f32 v[12:13], v[12:13], v[158:159], v[92:93] op_sel_hi:[1,0,1]
	v_pk_add_f32 v[64:65], v[64:65], 1.0 op_sel_hi:[1,0]
	v_pk_fma_f32 v[4:5], v[4:5], v[158:159], v[84:85] op_sel_hi:[1,0,1]
	v_rcp_f32_e32 v64, v64
	v_rcp_f32_e32 v65, v65
	v_pk_mul_f32 v[4:5], v[12:13], v[4:5]
	v_pk_fma_f32 v[6:7], v[6:7], v[158:159], v[86:87] op_sel_hi:[1,0,1]
	v_pk_fma_f32 v[8:9], v[8:9], v[158:159], v[88:89] op_sel_hi:[1,0,1]
	v_pk_mul_f32 v[74:75], v[66:67], v[64:65]
	v_cvt_pk_bf16_f32 v64, v68, v69
	v_mad_i64_i32 v[68:69], s[26:27], v98, s2, v[128:129]
	v_cvt_pk_bf16_f32 v65, v70, v71
	v_lshl_add_u64 v[68:69], v[68:69], 0, v[130:131]
	v_cvt_pk_bf16_f32 v66, v72, v73
	v_cvt_pk_bf16_f32 v67, v74, v75
	global_store_dwordx4 v[68:69], v[64:67], off
	v_pk_mul_f32 v[6:7], v[14:15], v[6:7]
	v_pk_fma_f32 v[0:1], v[0:1], v[158:159], v[80:81] op_sel_hi:[1,0,1]
	v_pk_mul_f32 v[64:65], v[60:61], s[88:89] op_sel_hi:[1,0]
	v_pk_mul_f32 v[60:61], v[62:63], s[88:89] op_sel_hi:[1,0]
	v_exp_f32_e32 v64, v64
	v_exp_f32_e32 v60, v60
	v_exp_f32_e32 v61, v61
	v_exp_f32_e32 v65, v65
	v_add_u32_e32 v66, 0x80, v165
	v_pk_fma_f32 v[10:11], v[10:11], v[158:159], v[90:91] op_sel_hi:[1,0,1]
	v_pk_add_f32 v[60:61], v[60:61], 1.0 op_sel_hi:[1,0]
	v_pk_add_f32 v[64:65], v[64:65], 1.0 op_sel_hi:[1,0]
	v_rcp_f32_e32 v60, v60
	v_rcp_f32_e32 v61, v61
	v_rcp_f32_e32 v64, v64
	v_rcp_f32_e32 v65, v65
	v_pk_mul_f32 v[0:1], v[8:9], v[0:1]
	v_pk_mul_f32 v[54:55], v[54:55], v[60:61]
	v_pk_mul_f32 v[60:61], v[56:57], s[88:89] op_sel_hi:[1,0]
	v_pk_mul_f32 v[52:53], v[52:53], v[64:65]
	v_exp_f32_e32 v60, v60
	v_exp_f32_e32 v61, v61
	v_pk_fma_f32 v[2:3], v[2:3], v[158:159], v[82:83] op_sel_hi:[1,0,1]
	s_andn2_b64 vcc, exec, s[36:37]
	v_pk_mul_f32 v[2:3], v[10:11], v[2:3]
	v_pk_add_f32 v[60:61], v[60:61], 1.0 op_sel_hi:[1,0]
	s_nop 0
	v_rcp_f32_e32 v60, v60
	v_rcp_f32_e32 v61, v61
	s_nop 0
	v_pk_mul_f32 v[56:57], v[48:49], v[60:61]
	v_pk_mul_f32 v[48:49], v[58:59], s[88:89] op_sel_hi:[1,0]
	s_nop 0
	v_exp_f32_e32 v48, v48
	v_exp_f32_e32 v49, v49
	s_nop 0
	v_pk_add_f32 v[48:49], v[48:49], 1.0 op_sel_hi:[1,0]
	s_nop 0
	v_rcp_f32_e32 v48, v48
	v_rcp_f32_e32 v49, v49
	s_nop 0
	v_pk_mul_f32 v[58:59], v[50:51], v[48:49]
	v_cvt_pk_bf16_f32 v48, v52, v53
; __device__ __forceinline__ unsigned cvt_pk_bf16(float lo, float hi) { unsigned r; asm volatile("v_cvt_pk_bf16_f32 %0, %1, %2" : "=v"(r) : "v"(lo), "v"(hi)); return r; }
; __device__ __forceinline__ f32x2 silu_mul_pk(f32x2 g, f32x2 u) {
;     const f32x2 t = g * (-1.4426950409f);
;     f32x2 e; e.x = __builtin_amdgcn_exp2f(t.x); e.y = __builtin_amdgcn_exp2f(t.y);
;     const f32x2 d = e + 1.0f;
;     f32x2 r; r.x = __builtin_amdgcn_rcpf(d.x); r.y = __builtin_amdgcn_rcpf(d.y);
;     return (g * u) * r;
; }
;     __device__ __forceinline__ void operator()(const f32x4 (&acc)[2][2][4][2], const pg8::Unit& u, int wr, int wc, int fr_, int fq_) const {
;     ...
;             for (int m = 0; m < 4; ++m) {
;                 const int lr = lrow0 + ai * 128 + m * 16;
;                 const float rs = rs8[ai * 4 + m];
;                 const f32x4 g0 = acc[ai][0][m][0] * rs + sv[0][0], g1 = acc[ai][0][m][1] * rs + sv[0][1];
;                 const f32x4 u0 = acc[ai][1][m][0] * rs + sv[1][0], u1 = acc[ai][1][m][1] * rs + sv[1][1];
;                 const f32x2 ha = pg8::silu_mul_pk((f32x2){g0[0], g0[1]}, (f32x2){u0[0], u0[1]}), hb = pg8::silu_mul_pk((f32x2){g0[2], g0[3]}, (f32x2){u0[2], u0[3]});
;                 const f32x2 hc = pg8::silu_mul_pk((f32x2){g1[0], g1[1]}, (f32x2){u1[0], u1[1]}), hd = pg8::silu_mul_pk((f32x2){g1[2], g1[3]}, (f32x2){u1[2], u1[3]});
;                 u32x4 w; w.x = cvt_pk_bf16(ha.x, ha.y); w.y = cvt_pk_bf16(hb.x, hb.y); w.z = cvt_pk_bf16(hc.x, hc.y); w.w = cvt_pk_bf16(hd.x, hd.y);
;                 *(u32x4*)(H + (size_t)lr * FF + hcol) = w;
;             }
	v_mad_i64_i32 v[52:53], s[26:27], v66, s2, v[128:129]
	v_cvt_pk_bf16_f32 v49, v54, v55
	v_lshl_add_u64 v[52:53], v[52:53], 0, v[130:131]
	v_cvt_pk_bf16_f32 v50, v56, v57
	v_cvt_pk_bf16_f32 v51, v58, v59
	global_store_dwordx4 v[52:53], v[48:51], off
	s_nop 1
	v_pk_mul_f32 v[48:49], v[44:45], s[88:89] op_sel_hi:[1,0]
	v_pk_mul_f32 v[44:45], v[46:47], s[88:89] op_sel_hi:[1,0]
	v_exp_f32_e32 v48, v48
	v_exp_f32_e32 v44, v44
	v_exp_f32_e32 v45, v45
	v_exp_f32_e32 v49, v49
	v_add_u32_e32 v50, 0x90, v165
	v_pk_add_f32 v[44:45], v[44:45], 1.0 op_sel_hi:[1,0]
	s_nop 0
	v_rcp_f32_e32 v44, v44
	v_rcp_f32_e32 v45, v45
	v_pk_add_f32 v[48:49], v[48:49], 1.0 op_sel_hi:[1,0]
	v_pk_mul_f32 v[38:39], v[38:39], v[44:45]
	v_pk_mul_f32 v[44:45], v[40:41], s[88:89] op_sel_hi:[1,0]
	v_rcp_f32_e32 v48, v48
	v_exp_f32_e32 v44, v44
	v_exp_f32_e32 v45, v45
	v_rcp_f32_e32 v49, v49
	v_pk_add_f32 v[44:45], v[44:45], 1.0 op_sel_hi:[1,0]
	s_nop 0
	v_rcp_f32_e32 v44, v44
	v_rcp_f32_e32 v45, v45
	v_pk_mul_f32 v[36:37], v[36:37], v[48:49]
	v_pk_mul_f32 v[40:41], v[32:33], v[44:45]
	v_pk_mul_f32 v[32:33], v[42:43], s[88:89] op_sel_hi:[1,0]
	s_nop 0
	v_exp_f32_e32 v32, v32
	v_exp_f32_e32 v33, v33
	s_nop 0
	v_pk_add_f32 v[32:33], v[32:33], 1.0 op_sel_hi:[1,0]
	s_nop 0
	v_rcp_f32_e32 v32, v32
	v_rcp_f32_e32 v33, v33
	s_nop 0
	v_pk_mul_f32 v[42:43], v[34:35], v[32:33]
	v_cvt_pk_bf16_f32 v32, v36, v37
	v_mad_i64_i32 v[36:37], s[26:27], v50, s2, v[128:129]
	v_cvt_pk_bf16_f32 v33, v38, v39
	v_lshl_add_u64 v[36:37], v[36:37], 0, v[130:131]
	v_cvt_pk_bf16_f32 v34, v40, v41
	v_cvt_pk_bf16_f32 v35, v42, v43
	global_store_dwordx4 v[36:37], v[32:35], off
	s_nop 1
	v_pk_mul_f32 v[32:33], v[28:29], s[88:89] op_sel_hi:[1,0]
	v_pk_mul_f32 v[28:29], v[30:31], s[88:89] op_sel_hi:[1,0]
	v_exp_f32_e32 v32, v32
	v_exp_f32_e32 v28, v28
	v_exp_f32_e32 v29, v29
	v_exp_f32_e32 v33, v33
	v_add_u32_e32 v34, 0xa0, v165
	v_pk_add_f32 v[28:29], v[28:29], 1.0 op_sel_hi:[1,0]
	s_nop 0
	v_rcp_f32_e32 v28, v28
	v_rcp_f32_e32 v29, v29
	v_pk_add_f32 v[32:33], v[32:33], 1.0 op_sel_hi:[1,0]
	v_pk_mul_f32 v[22:23], v[22:23], v[28:29]
	v_pk_mul_f32 v[28:29], v[24:25], s[88:89] op_sel_hi:[1,0]
	v_rcp_f32_e32 v32, v32
	v_exp_f32_e32 v28, v28
	v_exp_f32_e32 v29, v29
	v_rcp_f32_e32 v33, v33
	v_pk_add_f32 v[28:29], v[28:29], 1.0 op_sel_hi:[1,0]
	s_nop 0
	v_rcp_f32_e32 v28, v28
	v_rcp_f32_e32 v29, v29
	v_pk_mul_f32 v[20:21], v[20:21], v[32:33]
	v_pk_mul_f32 v[24:25], v[16:17], v[28:29]
	v_pk_mul_f32 v[16:17], v[26:27], s[88:89] op_sel_hi:[1,0]
	s_nop 0
	v_exp_f32_e32 v16, v16
	v_exp_f32_e32 v17, v17
	s_nop 0
	v_pk_add_f32 v[16:17], v[16:17], 1.0 op_sel_hi:[1,0]
	s_nop 0
	v_rcp_f32_e32 v16, v16
	v_rcp_f32_e32 v17, v17
	s_nop 0
	v_pk_mul_f32 v[26:27], v[18:19], v[16:17]
	v_cvt_pk_bf16_f32 v16, v20, v21
	v_mad_i64_i32 v[20:21], s[26:27], v34, s2, v[128:129]
	v_cvt_pk_bf16_f32 v17, v22, v23
	v_lshl_add_u64 v[20:21], v[20:21], 0, v[130:131]
	v_cvt_pk_bf16_f32 v18, v24, v25
	v_cvt_pk_bf16_f32 v19, v26, v27
	global_store_dwordx4 v[20:21], v[16:19], off
	s_nop 1
	v_pk_mul_f32 v[16:17], v[12:13], s[88:89] op_sel_hi:[1,0]
	v_pk_mul_f32 v[12:13], v[14:15], s[88:89] op_sel_hi:[1,0]
	v_exp_f32_e32 v16, v16
	v_exp_f32_e32 v12, v12
	v_exp_f32_e32 v13, v13
	v_exp_f32_e32 v17, v17
	v_add_u32_e32 v18, 0xb0, v165
	v_pk_add_f32 v[12:13], v[12:13], 1.0 op_sel_hi:[1,0]
	s_nop 0
	v_rcp_f32_e32 v12, v12
	v_rcp_f32_e32 v13, v13
	v_pk_add_f32 v[16:17], v[16:17], 1.0 op_sel_hi:[1,0]
	v_pk_mul_f32 v[6:7], v[6:7], v[12:13]
	v_pk_mul_f32 v[12:13], v[8:9], s[88:89] op_sel_hi:[1,0]
	v_rcp_f32_e32 v16, v16
	v_exp_f32_e32 v12, v12
	v_exp_f32_e32 v13, v13
	v_rcp_f32_e32 v17, v17
	v_pk_add_f32 v[12:13], v[12:13], 1.0 op_sel_hi:[1,0]
	s_nop 0
	v_rcp_f32_e32 v12, v12
	v_rcp_f32_e32 v13, v13
	v_pk_mul_f32 v[4:5], v[4:5], v[16:17]
	v_pk_mul_f32 v[8:9], v[0:1], v[12:13]
	v_pk_mul_f32 v[0:1], v[10:11], s[88:89] op_sel_hi:[1,0]
	s_nop 0
	v_exp_f32_e32 v0, v0
	v_exp_f32_e32 v1, v1
	s_nop 0
	v_pk_add_f32 v[0:1], v[0:1], 1.0 op_sel_hi:[1,0]
	s_nop 0
	v_rcp_f32_e32 v0, v0
	v_rcp_f32_e32 v1, v1
	s_nop 0
	v_pk_mul_f32 v[10:11], v[2:3], v[0:1]
	v_cvt_pk_bf16_f32 v0, v4, v5
	v_mad_i64_i32 v[4:5], s[26:27], v18, s2, v[128:129]
	v_lshl_add_u64 v[4:5], v[4:5], 0, v[130:131]
	s_mov_b64 s[26:27], -1
	v_cvt_pk_bf16_f32 v1, v6, v7
	v_cvt_pk_bf16_f32 v2, v8, v9
	v_cvt_pk_bf16_f32 v3, v10, v11
	global_store_dwordx4 v[4:5], v[0:3], off
	s_cbranch_vccnz .LBB0_369
	s_and_b64 vcc, exec, s[34:35]
	s_cbranch_vccnz .LBB0_368
	s_barrier
	s_branch .LBB0_368
